# cg grid sync replaced by hand-written single-counter release/acquire grid barrier (phase 0->1 seam), on v027
# baseline (speedup 1.0000x reference)
.LBB0_100:
	s_cmp_eq_u32 s75, 1
	s_cbranch_scc1 .LBB0_112
	s_waitcnt vmcnt(0) lgkmcnt(0)
	s_barrier
	v_cmp_eq_u32_e32 vcc, 0, v128
	s_and_saveexec_b64 s[0:1], vcc
	s_cbranch_execz .Lmy_gb_done
	buffer_wbl2 sc1
	s_waitcnt vmcnt(0)
	v_mov_b32_e32 v0, 0
	v_mov_b32_e32 v1, 1
	global_atomic_add v0, v1, s[70:71] offset:512
	s_mov_b32 s4, 0
.Lmy_gb_spin:
	global_load_dword v2, v0, s[70:71] offset:512 sc1
	s_waitcnt vmcnt(0)
	v_readfirstlane_b32 s5, v2
	s_add_u32 s4, s4, 1
	s_cmp_ge_u32 s5, s72
	s_cbranch_scc1 .Lmy_gb_ok
	s_sleep 1
	s_cmp_lt_u32 s4, 0x100000
	s_cbranch_scc1 .Lmy_gb_spin
.Lmy_gb_ok:
	buffer_inv sc1
	s_waitcnt vmcnt(0)
